# MLA K LDS-DMA without exec toggles (idle waves target a scratch LDS slot) and V pointer stepped by load immediates
# speedup vs baseline: 1.0137x; 1.0056x over previous
; #define AT_QK_LD0(kb_) do { if constexpr (NEGM) { const LAS unsigned char* kbp_ = Kl + (kb_) * KBUF + r32 * KROWB + hi * 16; AT_KLD2(0); __builtin_amdgcn_sched_barrier(0); } } while (0)
; template <int DQK, int DV, int RH, bool NEGM> ...
;     ...
;     const int NT = nkv / 64;
;     AT_GLOAD(0); AT_LSTORE(0, 0); __syncthreads();
;     int vs_prev = 2, vs_cur = 0, vs_next = 1;
;     if (!grpB) {
;         for (int t = 0; t < NT; ++t) {
;             const int kb = t & 1;
;             if (t + 1 < NT) AT_GLOAD(t + 1);
;             f32x16 p[RH][2];
;             AT_QK_LD0(kb); AT_QK(kb); AT_VLOAD(vs_cur); AT_SOFTMAX(); AT_PV(vs_cur);
;             if (t + 1 < NT) AT_LSTORE(kb ^ 1, vs_next);
.LBB0_881:
	s_or_b64 exec, exec, s[42:43]
	v_pk_add_f32 v[48:49], v[48:49], v[54:55]
	v_pk_add_f32 v[64:65], v[128:129], v[64:65]
	v_pk_add_f32 v[48:49], v[58:59], v[48:49] op_sel_hi:[0,1]
	v_pk_add_f32 v[52:53], v[52:53], v[56:57]
	v_pk_add_f32 v[48:49], v[64:65], v[48:49]
	v_pk_add_f32 v[70:71], v[118:119], v[70:71]
	v_pk_add_f32 v[48:49], v[52:53], v[48:49]
	v_add_u32_e32 v54, v136, v135
	v_pk_add_f32 v[150:151], v[70:71], v[48:49]
	v_add_u32_e32 v48, 0x8c00, v166
	s_waitcnt vmcnt(0)
	ds_write2_b64 v48, v[74:75], v[76:77] offset1:2
	v_mul_lo_u32 v48, v54, 12
	v_sub_u32_e32 v52, v133, v48
	s_lshr_b32 s21, s61, 4
	v_lshlrev_b32_e32 v48, 3, v52
	v_lshlrev_b32_e32 v175, 4, v52
	v_mov_b64_e32 v[52:53], s[40:41]
	s_and_b32 s42, s21, 7
	v_mul_lo_u32 v174, v54, s56
	v_mad_i64_i32 v[54:55], s[40:41], v54, s51, v[52:53]
	v_pk_add_f32 v[50:51], v[50:51], v[62:63]
	v_ashrrev_i32_e32 v49, 31, v48
	v_mad_u64_u32 v[54:55], s[40:41], s42, v163, v[54:55]
	v_pk_add_f32 v[66:67], v[130:131], v[66:67]
	v_pk_add_f32 v[50:51], v[58:59], v[50:51] op_sel_hi:[0,1]
	v_lshl_add_u64 v[48:49], v[48:49], 1, v[54:55]
	v_pk_add_f32 v[56:57], v[116:117], v[68:69]
	v_pk_add_f32 v[50:51], v[66:67], v[50:51]
	v_mov_b32_e32 v154, v48
	v_mad_i64_i32 v[48:49], s[40:41], v59, s51, v[52:53]
	v_pk_add_f32 v[60:61], v[60:61], v[72:73]
	v_pk_add_f32 v[50:51], v[56:57], v[50:51]
	s_lshl_b32 s43, s42, 6
	v_mad_u64_u32 v[48:49], s[40:41], s42, v163, v[48:49]
	v_pk_add_f32 v[152:153], v[60:61], v[50:51]
	v_lshlrev_b32_e32 v50, 3, v112
	s_add_i32 s40, s47, s43
	v_ashrrev_i32_e32 v51, 31, v50
	s_ashr_i32 s41, s40, 31
	v_lshl_add_u64 v[48:49], v[50:51], 1, v[48:49]
	s_lshl_b64 s[40:41], s[40:41], 13
	v_and_b32_e32 v50, 7, v132
	v_mov_b32_e32 v156, v48
	v_lshl_add_u64 v[48:49], v[78:79], 0, s[40:41]
	v_lshlrev_b32_e32 v148, 4, v50
	v_lshl_add_u64 v[48:49], v[48:49], 0, v[148:149]
	v_mul_u32_u24_e32 v173, 0x90, v134
	s_mov_b32 s21, 1
	v_mov_b32_e32 v158, v48
	s_mov_b32 s42, 2
	s_mov_b32 s43, 1
	s_waitcnt lgkmcnt(0)
	s_barrier
	s_mov_b64 s[98:99], s[28:29]
	s_mov_b64 s[100:101], s[30:31]
	v_add_u32_e32 v244, v174, v175
	v_add_u32_e32 v245, v171, v172
	s_mov_b32 s71, 0x13b13b14
	s_mov_b32 s72, 0x15555556
	v_add_u32_e32 v148, s79, v184
	v_mul_hi_u32 v160, v148, s71
	v_mul_u32_u24_e32 v161, 13, v160
	v_sub_u32_e32 v161, v148, v161
	v_min_u32_e32 v161, 11, v161
	v_mul_u32_u24_e32 v160, 0x600, v160
	v_lshl_add_u32 v241, v161, 4, v160
	v_mul_hi_u32 v160, v148, s72
	v_mul_u32_u24_e32 v161, 12, v160
	v_sub_u32_e32 v161, v148, v161
	v_mul_u32_u24_e32 v160, 0x600, v160
	v_lshl_add_u32 v160, v161, 4, v160
	v_sub_u32_e32 v241, v241, v160
	v_add_u32_e32 v241, v241, v154
	v_add_u32_e32 v148, 0x200, v148
	v_mul_hi_u32 v160, v148, s71
	v_mul_u32_u24_e32 v161, 13, v160
	v_sub_u32_e32 v161, v148, v161
	v_min_u32_e32 v161, 11, v161
	v_mul_u32_u24_e32 v160, 0x600, v160
	v_lshl_add_u32 v242, v161, 4, v160
	v_mul_hi_u32 v160, v148, s72
	v_mul_u32_u24_e32 v161, 12, v160
	v_sub_u32_e32 v161, v148, v161
	v_mul_u32_u24_e32 v160, 0x600, v160
	v_lshl_add_u32 v160, v161, 4, v160
	v_sub_u32_e32 v242, v242, v160
	v_add_u32_e32 v242, v242, v156
	s_lshl_b32 s70, s79, 4
	s_add_i32 s73, s70, 0x2000
	s_cmpk_lt_u32 s79, 0x140
	s_cselect_b32 s73, s73, 0x12000
	s_cselect_b32 s74, 0x3400, 0
	s_cmp_eq_u32 s65, 0
	s_cbranch_scc0 .Lmlac_loop

.Lmla_renorm_back:
	ds_read_b128 v[48:51], v169 offset:13312
	ds_read_b128 v[52:55], v169 offset:13344
	ds_read_b128 v[116:119], v169 offset:19968
	ds_read_b128 v[120:123], v169 offset:20000
	s_mov_b32 m0, s70
	s_nop 0
	global_load_lds_dwordx4 v241, s[98:99]
	s_mov_b32 m0, s73
	global_load_dwordx4 v[112:115], v158, s[100:101]
	global_load_lds_dwordx4 v242, s[98:99]
	s_add_u32 s98, s98, 0x18000
	s_addc_u32 s99, s99, 0
	s_waitcnt lgkmcnt(3)
	v_mfma_f32_32x32x16_bf16 v[64:79], v[48:51], v[100:103], v[32:47]
	ds_read_b128 v[124:127], v169 offset:13376
	ds_read_b128 v[128:131], v169 offset:13408
	ds_read_b128 v[132:135], v169 offset:20032
	ds_read_b128 v[136:139], v169 offset:20064
	s_waitcnt lgkmcnt(4)
	v_mfma_f32_32x32x16_bf16 v[64:79], v[52:55], v[96:99], v[64:79]
	v_mfma_f32_32x32x16_bf16 v[48:63], v[116:119], v[100:103], v[32:47]
	v_mfma_f32_32x32x16_bf16 v[48:63], v[120:123], v[96:99], v[48:63]
	s_waitcnt lgkmcnt(1)
	v_mfma_f32_32x32x16_bf16 v[64:79], v[124:127], v[92:95], v[64:79]
	v_mfma_f32_32x32x16_bf16 v[48:63], v[132:135], v[92:95], v[48:63]
	v_mfma_f32_32x32x16_bf16 v[64:79], v[128:131], v[88:91], v[64:79]
	ds_read_b128 v[116:119], v169 offset:13440
	ds_read_b128 v[120:123], v169 offset:13472
	ds_read_b128 v[128:131], v169 offset:20096
	ds_read_b128 v[176:179], v169 offset:20128
	s_waitcnt lgkmcnt(3)
	v_mfma_f32_32x32x16_bf16 v[48:63], v[136:139], v[88:91], v[48:63]
	v_mfma_f32_32x32x16_bf16 v[64:79], v[116:119], v[84:87], v[64:79]
	ds_read_b128 v[136:139], v170 offset:35840
	ds_read_b128 v[124:127], v170 offset:35872
	s_waitcnt lgkmcnt(3)
	v_mfma_f32_32x32x16_bf16 v[48:63], v[128:131], v[84:87], v[48:63]
	v_mfma_f32_32x32x16_bf16 v[64:79], v[120:123], v[80:83], v[64:79]
	ds_read_b128 v[132:135], v170 offset:35904
	ds_read_b128 v[120:123], v170 offset:35936
	ds_read_b128 v[144:147], v170 offset:40448
	ds_read_b128 v[140:143], v170 offset:40480
	ds_read_b128 v[128:131], v170 offset:40512
	ds_read_b128 v[116:119], v170 offset:40544
	s_waitcnt lgkmcnt(8)
	v_mfma_f32_32x32x16_bf16 v[48:63], v[176:179], v[80:83], v[48:63]
	s_add_i32 s43, s43, 1
	s_nop 3
	v_exp_f32_e32 v160, v64
	v_exp_f32_e32 v161, v65
	v_exp_f32_e32 v64, v66
	v_exp_f32_e32 v65, v67
	v_exp_f32_e32 v68, v68
	v_exp_f32_e32 v69, v69
	v_exp_f32_e32 v66, v70
	v_exp_f32_e32 v67, v71
	v_cvt_pk_bf16_f32 v176, v160, v161
	v_cvt_pk_bf16_f32 v177, v64, v65
	v_cvt_pk_bf16_f32 v178, v68, v69
	v_cvt_pk_bf16_f32 v179, v66, v67
	v_exp_f32_e32 v70, v74
	v_exp_f32_e32 v71, v75
	s_waitcnt lgkmcnt(0)
	v_mfma_f32_32x32x16_bf16 v[16:31], v[136:139], v[176:179], v[16:31]
	v_exp_f32_e32 v136, v72
	v_exp_f32_e32 v137, v73
	v_exp_f32_e32 v74, v76
	v_exp_f32_e32 v75, v77
	v_exp_f32_e32 v72, v78
	v_exp_f32_e32 v73, v79
	v_exp_f32_e32 v76, v48
	v_mfma_f32_32x32x16_bf16 v[0:15], v[144:147], v[176:179], v[0:15]
	v_cvt_pk_bf16_f32 v144, v136, v137
	v_cvt_pk_bf16_f32 v145, v70, v71
	v_cvt_pk_bf16_f32 v146, v74, v75
	v_cvt_pk_bf16_f32 v147, v72, v73
	v_exp_f32_e32 v77, v49
	v_exp_f32_e32 v48, v50
	v_exp_f32_e32 v49, v51
	v_mfma_f32_32x32x16_bf16 v[16:31], v[124:127], v[144:147], v[16:31]
	v_exp_f32_e32 v52, v52
	v_exp_f32_e32 v53, v53
	v_exp_f32_e32 v50, v54
	v_exp_f32_e32 v51, v55
	v_cvt_pk_bf16_f32 v124, v76, v77
	v_cvt_pk_bf16_f32 v125, v48, v49
	v_cvt_pk_bf16_f32 v126, v52, v53
	v_mfma_f32_32x32x16_bf16 v[0:15], v[140:143], v[144:147], v[0:15]
	v_cvt_pk_bf16_f32 v127, v50, v51
	v_exp_f32_e32 v78, v56
	v_exp_f32_e32 v79, v57
	v_exp_f32_e32 v54, v58
	v_exp_f32_e32 v55, v59
	v_exp_f32_e32 v58, v60
	v_exp_f32_e32 v59, v61
	v_mfma_f32_32x32x16_bf16 v[16:31], v[132:135], v[124:127], v[16:31]
	v_exp_f32_e32 v56, v62
	v_exp_f32_e32 v57, v63
	v_cvt_pk_bf16_f32 v60, v78, v79
	v_cvt_pk_bf16_f32 v61, v54, v55
	v_cvt_pk_bf16_f32 v62, v58, v59
	v_cvt_pk_bf16_f32 v63, v56, v57
	v_mfma_f32_32x32x16_bf16 v[0:15], v[128:131], v[124:127], v[0:15]
	v_mfma_f32_32x32x16_bf16 v[16:31], v[120:123], v[60:63], v[16:31]
	v_mfma_f32_32x32x16_bf16 v[0:15], v[116:119], v[60:63], v[0:15]
	s_waitcnt vmcnt(0)
	ds_write2_b64 v247, v[112:113], v[114:115] offset1:2
	v_pk_add_f32 v[48:49], v[64:65], v[48:49]
	v_pk_add_f32 v[60:61], v[160:161], v[76:77]
	v_pk_add_f32 v[48:49], v[152:153], v[48:49]
	v_pk_add_f32 v[50:51], v[66:67], v[50:51]
	v_pk_add_f32 v[60:61], v[150:151], v[60:61]
	v_pk_add_f32 v[52:53], v[68:69], v[52:53]
	v_pk_add_f32 v[48:49], v[50:51], v[48:49]
	v_pk_add_f32 v[50:51], v[70:71], v[54:55]
	v_pk_add_f32 v[52:53], v[52:53], v[60:61]
	v_pk_add_f32 v[60:61], v[136:137], v[78:79]
	v_pk_add_f32 v[48:49], v[50:51], v[48:49]
	v_pk_add_f32 v[50:51], v[72:73], v[56:57]
	v_pk_add_f32 v[52:53], v[60:61], v[52:53]
	v_pk_add_f32 v[58:59], v[74:75], v[58:59]
	v_pk_add_f32 v[152:153], v[50:51], v[48:49]
	v_pk_add_f32 v[150:151], v[58:59], v[52:53]
	s_waitcnt lgkmcnt(0)
	s_barrier
	ds_read_b128 v[48:51], v169
	ds_read_b128 v[52:55], v169 offset:32
	ds_read_b128 v[116:119], v169 offset:6656
	ds_read_b128 v[120:123], v169 offset:6688
	s_add_i32 m0, s70, 13312
	s_nop 0
	global_load_lds_dwordx4 v241, s[98:99]
	s_add_i32 m0, s73, s74
	global_load_dwordx4 v[112:115], v158, s[100:101] offset:128
	global_load_lds_dwordx4 v242, s[98:99]
	s_add_u32 s98, s98, 0x18000
	s_addc_u32 s99, s99, 0
	s_waitcnt lgkmcnt(3)
	v_mfma_f32_32x32x16_bf16 v[64:79], v[48:51], v[100:103], v[32:47]
	ds_read_b128 v[124:127], v169 offset:64
	ds_read_b128 v[128:131], v169 offset:96
	ds_read_b128 v[132:135], v169 offset:6720
	ds_read_b128 v[136:139], v169 offset:6752
	s_waitcnt lgkmcnt(4)
	v_mfma_f32_32x32x16_bf16 v[64:79], v[52:55], v[96:99], v[64:79]
	v_mfma_f32_32x32x16_bf16 v[48:63], v[116:119], v[100:103], v[32:47]
	v_mfma_f32_32x32x16_bf16 v[48:63], v[120:123], v[96:99], v[48:63]
	s_waitcnt lgkmcnt(1)
	v_mfma_f32_32x32x16_bf16 v[64:79], v[124:127], v[92:95], v[64:79]
	v_mfma_f32_32x32x16_bf16 v[48:63], v[132:135], v[92:95], v[48:63]
	v_mfma_f32_32x32x16_bf16 v[64:79], v[128:131], v[88:91], v[64:79]
	ds_read_b128 v[116:119], v169 offset:128
	ds_read_b128 v[120:123], v169 offset:160
	ds_read_b128 v[128:131], v169 offset:6784
	ds_read_b128 v[176:179], v169 offset:6816
	s_waitcnt lgkmcnt(3)
	v_mfma_f32_32x32x16_bf16 v[48:63], v[136:139], v[88:91], v[48:63]
	v_mfma_f32_32x32x16_bf16 v[64:79], v[116:119], v[84:87], v[64:79]
	ds_read_b128 v[136:139], v170 offset:45056
	ds_read_b128 v[124:127], v170 offset:45088
	s_waitcnt lgkmcnt(3)
	v_mfma_f32_32x32x16_bf16 v[48:63], v[128:131], v[84:87], v[48:63]
	v_mfma_f32_32x32x16_bf16 v[64:79], v[120:123], v[80:83], v[64:79]
	ds_read_b128 v[132:135], v170 offset:45120
	ds_read_b128 v[120:123], v170 offset:45152
	ds_read_b128 v[144:147], v170 offset:49664
	ds_read_b128 v[140:143], v170 offset:49696
	ds_read_b128 v[128:131], v170 offset:49728
	ds_read_b128 v[116:119], v170 offset:49760
	s_waitcnt lgkmcnt(8)
	v_mfma_f32_32x32x16_bf16 v[48:63], v[176:179], v[80:83], v[48:63]
	s_add_i32 s43, s43, 1
	s_nop 3
	v_exp_f32_e32 v160, v64
	v_exp_f32_e32 v161, v65
	v_exp_f32_e32 v64, v66
	v_exp_f32_e32 v65, v67
	v_exp_f32_e32 v68, v68
	v_exp_f32_e32 v69, v69
	v_exp_f32_e32 v66, v70
	v_exp_f32_e32 v67, v71
	v_cvt_pk_bf16_f32 v176, v160, v161
	v_cvt_pk_bf16_f32 v177, v64, v65
	v_cvt_pk_bf16_f32 v178, v68, v69
	v_cvt_pk_bf16_f32 v179, v66, v67
	v_exp_f32_e32 v70, v74
	v_exp_f32_e32 v71, v75
	s_waitcnt lgkmcnt(0)
	v_mfma_f32_32x32x16_bf16 v[16:31], v[136:139], v[176:179], v[16:31]
	v_exp_f32_e32 v136, v72
	v_exp_f32_e32 v137, v73
	v_exp_f32_e32 v74, v76
	v_exp_f32_e32 v75, v77
	v_exp_f32_e32 v72, v78
	v_exp_f32_e32 v73, v79
	v_exp_f32_e32 v76, v48
	v_mfma_f32_32x32x16_bf16 v[0:15], v[144:147], v[176:179], v[0:15]
	v_cvt_pk_bf16_f32 v144, v136, v137
	v_cvt_pk_bf16_f32 v145, v70, v71
	v_cvt_pk_bf16_f32 v146, v74, v75
	v_cvt_pk_bf16_f32 v147, v72, v73
	v_exp_f32_e32 v77, v49
	v_exp_f32_e32 v48, v50
	v_exp_f32_e32 v49, v51
	v_mfma_f32_32x32x16_bf16 v[16:31], v[124:127], v[144:147], v[16:31]
	v_exp_f32_e32 v52, v52
	v_exp_f32_e32 v53, v53
	v_exp_f32_e32 v50, v54
	v_exp_f32_e32 v51, v55
	v_cvt_pk_bf16_f32 v124, v76, v77
	v_cvt_pk_bf16_f32 v125, v48, v49
	v_cvt_pk_bf16_f32 v126, v52, v53
	v_mfma_f32_32x32x16_bf16 v[0:15], v[140:143], v[144:147], v[0:15]
	v_cvt_pk_bf16_f32 v127, v50, v51
	v_exp_f32_e32 v78, v56
	v_exp_f32_e32 v79, v57
	v_exp_f32_e32 v54, v58
	v_exp_f32_e32 v55, v59
	v_exp_f32_e32 v58, v60
	v_exp_f32_e32 v59, v61
	v_mfma_f32_32x32x16_bf16 v[16:31], v[132:135], v[124:127], v[16:31]
	v_exp_f32_e32 v56, v62
	v_exp_f32_e32 v57, v63
	v_cvt_pk_bf16_f32 v60, v78, v79
	v_cvt_pk_bf16_f32 v61, v54, v55
	v_cvt_pk_bf16_f32 v62, v58, v59
	v_cvt_pk_bf16_f32 v63, v56, v57
	v_mfma_f32_32x32x16_bf16 v[0:15], v[128:131], v[124:127], v[0:15]
	v_mfma_f32_32x32x16_bf16 v[16:31], v[120:123], v[60:63], v[16:31]
	v_mfma_f32_32x32x16_bf16 v[0:15], v[116:119], v[60:63], v[0:15]
	s_waitcnt vmcnt(0)
	ds_write2_b64 v243, v[112:113], v[114:115] offset1:2
	v_pk_add_f32 v[48:49], v[64:65], v[48:49]
	v_pk_add_f32 v[60:61], v[160:161], v[76:77]
	v_pk_add_f32 v[48:49], v[152:153], v[48:49]
	v_pk_add_f32 v[50:51], v[66:67], v[50:51]
	v_pk_add_f32 v[60:61], v[150:151], v[60:61]
	v_pk_add_f32 v[52:53], v[68:69], v[52:53]
	v_pk_add_f32 v[48:49], v[50:51], v[48:49]
	v_pk_add_f32 v[50:51], v[70:71], v[54:55]
	v_pk_add_f32 v[52:53], v[52:53], v[60:61]
	v_pk_add_f32 v[60:61], v[136:137], v[78:79]
	v_pk_add_f32 v[48:49], v[50:51], v[48:49]
	v_pk_add_f32 v[50:51], v[72:73], v[56:57]
	v_pk_add_f32 v[52:53], v[60:61], v[52:53]
	v_pk_add_f32 v[58:59], v[74:75], v[58:59]
	v_pk_add_f32 v[152:153], v[50:51], v[48:49]
	v_pk_add_f32 v[150:151], v[58:59], v[52:53]
	s_cmp_lg_u32 s43, 63
	s_waitcnt lgkmcnt(0)
	s_barrier
	s_cbranch_scc0 .Lmla_exit
	ds_read_b128 v[48:51], v169 offset:13312
	ds_read_b128 v[52:55], v169 offset:13344
	ds_read_b128 v[116:119], v169 offset:19968
	ds_read_b128 v[120:123], v169 offset:20000
	s_mov_b32 m0, s70
	s_nop 0
	global_load_lds_dwordx4 v241, s[98:99]
	s_mov_b32 m0, s73
	global_load_dwordx4 v[112:115], v158, s[100:101] offset:256
	global_load_lds_dwordx4 v242, s[98:99]
	s_add_u32 s98, s98, 0x18000
	s_addc_u32 s99, s99, 0
	s_waitcnt lgkmcnt(3)
	v_mfma_f32_32x32x16_bf16 v[64:79], v[48:51], v[100:103], v[32:47]
	ds_read_b128 v[124:127], v169 offset:13376
	ds_read_b128 v[128:131], v169 offset:13408
	ds_read_b128 v[132:135], v169 offset:20032
	ds_read_b128 v[136:139], v169 offset:20064
	s_waitcnt lgkmcnt(4)
	v_mfma_f32_32x32x16_bf16 v[64:79], v[52:55], v[96:99], v[64:79]
	v_mfma_f32_32x32x16_bf16 v[48:63], v[116:119], v[100:103], v[32:47]
	v_mfma_f32_32x32x16_bf16 v[48:63], v[120:123], v[96:99], v[48:63]
	s_waitcnt lgkmcnt(1)
	v_mfma_f32_32x32x16_bf16 v[64:79], v[124:127], v[92:95], v[64:79]
	v_mfma_f32_32x32x16_bf16 v[48:63], v[132:135], v[92:95], v[48:63]
	v_mfma_f32_32x32x16_bf16 v[64:79], v[128:131], v[88:91], v[64:79]
	ds_read_b128 v[116:119], v169 offset:13440
	ds_read_b128 v[120:123], v169 offset:13472
	ds_read_b128 v[128:131], v169 offset:20096
	ds_read_b128 v[176:179], v169 offset:20128
	s_waitcnt lgkmcnt(3)
	v_mfma_f32_32x32x16_bf16 v[48:63], v[136:139], v[88:91], v[48:63]
	v_mfma_f32_32x32x16_bf16 v[64:79], v[116:119], v[84:87], v[64:79]
	ds_read_b128 v[136:139], v170 offset:26624
	ds_read_b128 v[124:127], v170 offset:26656
	s_waitcnt lgkmcnt(3)
	v_mfma_f32_32x32x16_bf16 v[48:63], v[128:131], v[84:87], v[48:63]
	v_mfma_f32_32x32x16_bf16 v[64:79], v[120:123], v[80:83], v[64:79]
	ds_read_b128 v[132:135], v170 offset:26688
	ds_read_b128 v[120:123], v170 offset:26720
	ds_read_b128 v[144:147], v170 offset:31232
	ds_read_b128 v[140:143], v170 offset:31264
	ds_read_b128 v[128:131], v170 offset:31296
	ds_read_b128 v[116:119], v170 offset:31328
	s_waitcnt lgkmcnt(8)
	v_mfma_f32_32x32x16_bf16 v[48:63], v[176:179], v[80:83], v[48:63]
	s_add_i32 s43, s43, 1
	s_nop 3
	v_exp_f32_e32 v160, v64
	v_exp_f32_e32 v161, v65
	v_exp_f32_e32 v64, v66
	v_exp_f32_e32 v65, v67
	v_exp_f32_e32 v68, v68
	v_exp_f32_e32 v69, v69
	v_exp_f32_e32 v66, v70
	v_exp_f32_e32 v67, v71
	v_cvt_pk_bf16_f32 v176, v160, v161
	v_cvt_pk_bf16_f32 v177, v64, v65
	v_cvt_pk_bf16_f32 v178, v68, v69
	v_cvt_pk_bf16_f32 v179, v66, v67
	v_exp_f32_e32 v70, v74
	v_exp_f32_e32 v71, v75
	s_waitcnt lgkmcnt(0)
	v_mfma_f32_32x32x16_bf16 v[16:31], v[136:139], v[176:179], v[16:31]
	v_exp_f32_e32 v136, v72
	v_exp_f32_e32 v137, v73
	v_exp_f32_e32 v74, v76
	v_exp_f32_e32 v75, v77
	v_exp_f32_e32 v72, v78
	v_exp_f32_e32 v73, v79
	v_exp_f32_e32 v76, v48
	v_mfma_f32_32x32x16_bf16 v[0:15], v[144:147], v[176:179], v[0:15]
	v_cvt_pk_bf16_f32 v144, v136, v137
	v_cvt_pk_bf16_f32 v145, v70, v71
	v_cvt_pk_bf16_f32 v146, v74, v75
	v_cvt_pk_bf16_f32 v147, v72, v73
	v_exp_f32_e32 v77, v49
	v_exp_f32_e32 v48, v50
	v_exp_f32_e32 v49, v51
	v_mfma_f32_32x32x16_bf16 v[16:31], v[124:127], v[144:147], v[16:31]
	v_exp_f32_e32 v52, v52
	v_exp_f32_e32 v53, v53
	v_exp_f32_e32 v50, v54
	v_exp_f32_e32 v51, v55
	v_cvt_pk_bf16_f32 v124, v76, v77
	v_cvt_pk_bf16_f32 v125, v48, v49
	v_cvt_pk_bf16_f32 v126, v52, v53
	v_mfma_f32_32x32x16_bf16 v[0:15], v[140:143], v[144:147], v[0:15]
	v_cvt_pk_bf16_f32 v127, v50, v51
	v_exp_f32_e32 v78, v56
	v_exp_f32_e32 v79, v57
	v_exp_f32_e32 v54, v58
	v_exp_f32_e32 v55, v59
	v_exp_f32_e32 v58, v60
	v_exp_f32_e32 v59, v61
	v_mfma_f32_32x32x16_bf16 v[16:31], v[132:135], v[124:127], v[16:31]
	v_exp_f32_e32 v56, v62
	v_exp_f32_e32 v57, v63
	v_cvt_pk_bf16_f32 v60, v78, v79
	v_cvt_pk_bf16_f32 v61, v54, v55
	v_cvt_pk_bf16_f32 v62, v58, v59
	v_cvt_pk_bf16_f32 v63, v56, v57
	v_mfma_f32_32x32x16_bf16 v[0:15], v[128:131], v[124:127], v[0:15]
	v_mfma_f32_32x32x16_bf16 v[16:31], v[120:123], v[60:63], v[16:31]
	v_mfma_f32_32x32x16_bf16 v[0:15], v[116:119], v[60:63], v[0:15]
	s_waitcnt vmcnt(0)
	ds_write2_b64 v246, v[112:113], v[114:115] offset1:2
	v_pk_add_f32 v[48:49], v[64:65], v[48:49]
	v_pk_add_f32 v[60:61], v[160:161], v[76:77]
	v_pk_add_f32 v[48:49], v[152:153], v[48:49]
	v_pk_add_f32 v[50:51], v[66:67], v[50:51]
	v_pk_add_f32 v[60:61], v[150:151], v[60:61]
	v_pk_add_f32 v[52:53], v[68:69], v[52:53]
	v_pk_add_f32 v[48:49], v[50:51], v[48:49]
	v_pk_add_f32 v[50:51], v[70:71], v[54:55]
	v_pk_add_f32 v[52:53], v[52:53], v[60:61]
	v_pk_add_f32 v[60:61], v[136:137], v[78:79]
	v_pk_add_f32 v[48:49], v[50:51], v[48:49]
	v_pk_add_f32 v[50:51], v[72:73], v[56:57]
	v_pk_add_f32 v[52:53], v[60:61], v[52:53]
	v_pk_add_f32 v[58:59], v[74:75], v[58:59]
	v_pk_add_f32 v[152:153], v[50:51], v[48:49]
	v_pk_add_f32 v[150:151], v[58:59], v[52:53]
	s_waitcnt lgkmcnt(0)
	s_barrier
	ds_read_b128 v[48:51], v169
	ds_read_b128 v[52:55], v169 offset:32
	ds_read_b128 v[116:119], v169 offset:6656
	ds_read_b128 v[120:123], v169 offset:6688
	s_add_i32 m0, s70, 13312
	s_nop 0
	global_load_lds_dwordx4 v241, s[98:99]
	s_add_i32 m0, s73, s74
	global_load_dwordx4 v[112:115], v158, s[100:101] offset:384
	global_load_lds_dwordx4 v242, s[98:99]
	s_add_u32 s98, s98, 0x18000
	s_addc_u32 s99, s99, 0
	s_waitcnt lgkmcnt(3)
	v_mfma_f32_32x32x16_bf16 v[64:79], v[48:51], v[100:103], v[32:47]
	ds_read_b128 v[124:127], v169 offset:64
	ds_read_b128 v[128:131], v169 offset:96
	ds_read_b128 v[132:135], v169 offset:6720
	ds_read_b128 v[136:139], v169 offset:6752
	s_waitcnt lgkmcnt(4)
	v_mfma_f32_32x32x16_bf16 v[64:79], v[52:55], v[96:99], v[64:79]
	v_mfma_f32_32x32x16_bf16 v[48:63], v[116:119], v[100:103], v[32:47]
	v_mfma_f32_32x32x16_bf16 v[48:63], v[120:123], v[96:99], v[48:63]
	s_waitcnt lgkmcnt(1)
	v_mfma_f32_32x32x16_bf16 v[64:79], v[124:127], v[92:95], v[64:79]
	v_mfma_f32_32x32x16_bf16 v[48:63], v[132:135], v[92:95], v[48:63]
	v_mfma_f32_32x32x16_bf16 v[64:79], v[128:131], v[88:91], v[64:79]
	ds_read_b128 v[116:119], v169 offset:128
	ds_read_b128 v[120:123], v169 offset:160
	ds_read_b128 v[128:131], v169 offset:6784
	ds_read_b128 v[176:179], v169 offset:6816
	s_waitcnt lgkmcnt(3)
	v_mfma_f32_32x32x16_bf16 v[48:63], v[136:139], v[88:91], v[48:63]
	v_mfma_f32_32x32x16_bf16 v[64:79], v[116:119], v[84:87], v[64:79]
	ds_read_b128 v[136:139], v170 offset:35840
	ds_read_b128 v[124:127], v170 offset:35872
	s_waitcnt lgkmcnt(3)
	v_mfma_f32_32x32x16_bf16 v[48:63], v[128:131], v[84:87], v[48:63]
	v_mfma_f32_32x32x16_bf16 v[64:79], v[120:123], v[80:83], v[64:79]
	ds_read_b128 v[132:135], v170 offset:35904
	ds_read_b128 v[120:123], v170 offset:35936
	ds_read_b128 v[144:147], v170 offset:40448
	ds_read_b128 v[140:143], v170 offset:40480
	ds_read_b128 v[128:131], v170 offset:40512
	ds_read_b128 v[116:119], v170 offset:40544
	s_waitcnt lgkmcnt(8)
	v_mfma_f32_32x32x16_bf16 v[48:63], v[176:179], v[80:83], v[48:63]
	s_add_i32 s43, s43, 1
	s_nop 3
	v_exp_f32_e32 v160, v64
	v_exp_f32_e32 v161, v65
	v_exp_f32_e32 v64, v66
	v_exp_f32_e32 v65, v67
	v_exp_f32_e32 v68, v68
	v_exp_f32_e32 v69, v69
	v_exp_f32_e32 v66, v70
	v_exp_f32_e32 v67, v71
	v_cvt_pk_bf16_f32 v176, v160, v161
	v_cvt_pk_bf16_f32 v177, v64, v65
	v_cvt_pk_bf16_f32 v178, v68, v69
	v_cvt_pk_bf16_f32 v179, v66, v67
	v_exp_f32_e32 v70, v74
	v_exp_f32_e32 v71, v75
	s_waitcnt lgkmcnt(0)
	v_mfma_f32_32x32x16_bf16 v[16:31], v[136:139], v[176:179], v[16:31]
	v_exp_f32_e32 v136, v72
	v_exp_f32_e32 v137, v73
	v_exp_f32_e32 v74, v76
	v_exp_f32_e32 v75, v77
	v_exp_f32_e32 v72, v78
	v_exp_f32_e32 v73, v79
	v_exp_f32_e32 v76, v48
	v_mfma_f32_32x32x16_bf16 v[0:15], v[144:147], v[176:179], v[0:15]
	v_cvt_pk_bf16_f32 v144, v136, v137
	v_cvt_pk_bf16_f32 v145, v70, v71
	v_cvt_pk_bf16_f32 v146, v74, v75
	v_cvt_pk_bf16_f32 v147, v72, v73
	v_exp_f32_e32 v77, v49
	v_exp_f32_e32 v48, v50
	v_exp_f32_e32 v49, v51
	v_mfma_f32_32x32x16_bf16 v[16:31], v[124:127], v[144:147], v[16:31]
	v_exp_f32_e32 v52, v52
	v_exp_f32_e32 v53, v53
	v_exp_f32_e32 v50, v54
	v_exp_f32_e32 v51, v55
	v_cvt_pk_bf16_f32 v124, v76, v77
	v_cvt_pk_bf16_f32 v125, v48, v49
	v_cvt_pk_bf16_f32 v126, v52, v53
	v_mfma_f32_32x32x16_bf16 v[0:15], v[140:143], v[144:147], v[0:15]
	v_cvt_pk_bf16_f32 v127, v50, v51
	v_exp_f32_e32 v78, v56
	v_exp_f32_e32 v79, v57
	v_exp_f32_e32 v54, v58
	v_exp_f32_e32 v55, v59
	v_exp_f32_e32 v58, v60
	v_exp_f32_e32 v59, v61
	v_mfma_f32_32x32x16_bf16 v[16:31], v[132:135], v[124:127], v[16:31]
	v_exp_f32_e32 v56, v62
	v_exp_f32_e32 v57, v63
	v_cvt_pk_bf16_f32 v60, v78, v79
	v_cvt_pk_bf16_f32 v61, v54, v55
	v_cvt_pk_bf16_f32 v62, v58, v59
	v_cvt_pk_bf16_f32 v63, v56, v57
	v_mfma_f32_32x32x16_bf16 v[0:15], v[128:131], v[124:127], v[0:15]
	v_mfma_f32_32x32x16_bf16 v[16:31], v[120:123], v[60:63], v[16:31]
	v_mfma_f32_32x32x16_bf16 v[0:15], v[116:119], v[60:63], v[0:15]
	s_waitcnt vmcnt(0)
	ds_write2_b64 v247, v[112:113], v[114:115] offset1:2
	v_pk_add_f32 v[48:49], v[64:65], v[48:49]
	v_pk_add_f32 v[60:61], v[160:161], v[76:77]
	v_pk_add_f32 v[48:49], v[152:153], v[48:49]
	v_pk_add_f32 v[50:51], v[66:67], v[50:51]
	v_pk_add_f32 v[60:61], v[150:151], v[60:61]
	v_pk_add_f32 v[52:53], v[68:69], v[52:53]
	v_pk_add_f32 v[48:49], v[50:51], v[48:49]
	v_pk_add_f32 v[50:51], v[70:71], v[54:55]
	v_pk_add_f32 v[52:53], v[52:53], v[60:61]
	v_pk_add_f32 v[60:61], v[136:137], v[78:79]
	v_pk_add_f32 v[48:49], v[50:51], v[48:49]
	v_pk_add_f32 v[50:51], v[72:73], v[56:57]
	v_pk_add_f32 v[52:53], v[60:61], v[52:53]
	v_pk_add_f32 v[58:59], v[74:75], v[58:59]
	v_pk_add_f32 v[152:153], v[50:51], v[48:49]
	v_pk_add_f32 v[150:151], v[58:59], v[52:53]
	s_waitcnt lgkmcnt(0)
	s_barrier
	ds_read_b128 v[48:51], v169 offset:13312
	ds_read_b128 v[52:55], v169 offset:13344
	ds_read_b128 v[116:119], v169 offset:19968
	ds_read_b128 v[120:123], v169 offset:20000
	s_mov_b32 m0, s70
	s_nop 0
	global_load_lds_dwordx4 v241, s[98:99]
	s_mov_b32 m0, s73
	global_load_dwordx4 v[112:115], v158, s[100:101] offset:512
	global_load_lds_dwordx4 v242, s[98:99]
	s_add_u32 s98, s98, 0x18000
	s_addc_u32 s99, s99, 0
	s_waitcnt lgkmcnt(3)
	v_mfma_f32_32x32x16_bf16 v[64:79], v[48:51], v[100:103], v[32:47]
	ds_read_b128 v[124:127], v169 offset:13376
	ds_read_b128 v[128:131], v169 offset:13408
	ds_read_b128 v[132:135], v169 offset:20032
	ds_read_b128 v[136:139], v169 offset:20064
	s_waitcnt lgkmcnt(4)
	v_mfma_f32_32x32x16_bf16 v[64:79], v[52:55], v[96:99], v[64:79]
	v_mfma_f32_32x32x16_bf16 v[48:63], v[116:119], v[100:103], v[32:47]
	v_mfma_f32_32x32x16_bf16 v[48:63], v[120:123], v[96:99], v[48:63]
	s_waitcnt lgkmcnt(1)
	v_mfma_f32_32x32x16_bf16 v[64:79], v[124:127], v[92:95], v[64:79]
	v_mfma_f32_32x32x16_bf16 v[48:63], v[132:135], v[92:95], v[48:63]
	v_mfma_f32_32x32x16_bf16 v[64:79], v[128:131], v[88:91], v[64:79]
	ds_read_b128 v[116:119], v169 offset:13440
	ds_read_b128 v[120:123], v169 offset:13472
	ds_read_b128 v[128:131], v169 offset:20096
	ds_read_b128 v[176:179], v169 offset:20128
	s_waitcnt lgkmcnt(3)
	v_mfma_f32_32x32x16_bf16 v[48:63], v[136:139], v[88:91], v[48:63]
	v_mfma_f32_32x32x16_bf16 v[64:79], v[116:119], v[84:87], v[64:79]
	ds_read_b128 v[136:139], v170 offset:45056
	ds_read_b128 v[124:127], v170 offset:45088
	s_waitcnt lgkmcnt(3)
	v_mfma_f32_32x32x16_bf16 v[48:63], v[128:131], v[84:87], v[48:63]
	v_mfma_f32_32x32x16_bf16 v[64:79], v[120:123], v[80:83], v[64:79]
	ds_read_b128 v[132:135], v170 offset:45120
	ds_read_b128 v[120:123], v170 offset:45152
	ds_read_b128 v[144:147], v170 offset:49664
	ds_read_b128 v[140:143], v170 offset:49696
	ds_read_b128 v[128:131], v170 offset:49728
	ds_read_b128 v[116:119], v170 offset:49760
	s_waitcnt lgkmcnt(8)
	v_mfma_f32_32x32x16_bf16 v[48:63], v[176:179], v[80:83], v[48:63]
	s_add_i32 s43, s43, 1
	s_nop 3
	v_exp_f32_e32 v160, v64
	v_exp_f32_e32 v161, v65
	v_exp_f32_e32 v64, v66
	v_exp_f32_e32 v65, v67
	v_exp_f32_e32 v68, v68
	v_exp_f32_e32 v69, v69
	v_exp_f32_e32 v66, v70
	v_exp_f32_e32 v67, v71
	v_cvt_pk_bf16_f32 v176, v160, v161
	v_cvt_pk_bf16_f32 v177, v64, v65
	v_cvt_pk_bf16_f32 v178, v68, v69
	v_cvt_pk_bf16_f32 v179, v66, v67
	v_exp_f32_e32 v70, v74
	v_exp_f32_e32 v71, v75
	s_waitcnt lgkmcnt(0)
	v_mfma_f32_32x32x16_bf16 v[16:31], v[136:139], v[176:179], v[16:31]
	v_exp_f32_e32 v136, v72
	v_exp_f32_e32 v137, v73
	v_exp_f32_e32 v74, v76
	v_exp_f32_e32 v75, v77
	v_exp_f32_e32 v72, v78
	v_exp_f32_e32 v73, v79
	v_exp_f32_e32 v76, v48
	v_mfma_f32_32x32x16_bf16 v[0:15], v[144:147], v[176:179], v[0:15]
	v_cvt_pk_bf16_f32 v144, v136, v137
	v_cvt_pk_bf16_f32 v145, v70, v71
	v_cvt_pk_bf16_f32 v146, v74, v75
	v_cvt_pk_bf16_f32 v147, v72, v73
	v_exp_f32_e32 v77, v49
	v_exp_f32_e32 v48, v50
	v_exp_f32_e32 v49, v51
	v_mfma_f32_32x32x16_bf16 v[16:31], v[124:127], v[144:147], v[16:31]
	v_exp_f32_e32 v52, v52
	v_exp_f32_e32 v53, v53
	v_exp_f32_e32 v50, v54
	v_exp_f32_e32 v51, v55
	v_cvt_pk_bf16_f32 v124, v76, v77
	v_cvt_pk_bf16_f32 v125, v48, v49
	v_cvt_pk_bf16_f32 v126, v52, v53
	v_mfma_f32_32x32x16_bf16 v[0:15], v[140:143], v[144:147], v[0:15]
	v_cvt_pk_bf16_f32 v127, v50, v51
	v_exp_f32_e32 v78, v56
	v_exp_f32_e32 v79, v57
	v_exp_f32_e32 v54, v58
	v_exp_f32_e32 v55, v59
	v_exp_f32_e32 v58, v60
	v_exp_f32_e32 v59, v61
	v_mfma_f32_32x32x16_bf16 v[16:31], v[132:135], v[124:127], v[16:31]
	v_exp_f32_e32 v56, v62
	v_exp_f32_e32 v57, v63
	v_cvt_pk_bf16_f32 v60, v78, v79
	v_cvt_pk_bf16_f32 v61, v54, v55
	v_cvt_pk_bf16_f32 v62, v58, v59
	v_cvt_pk_bf16_f32 v63, v56, v57
	v_mfma_f32_32x32x16_bf16 v[0:15], v[128:131], v[124:127], v[0:15]
	v_mfma_f32_32x32x16_bf16 v[16:31], v[120:123], v[60:63], v[16:31]
	v_mfma_f32_32x32x16_bf16 v[0:15], v[116:119], v[60:63], v[0:15]
	s_waitcnt vmcnt(0)
	ds_write2_b64 v243, v[112:113], v[114:115] offset1:2
	v_pk_add_f32 v[48:49], v[64:65], v[48:49]
	v_pk_add_f32 v[60:61], v[160:161], v[76:77]
	v_pk_add_f32 v[48:49], v[152:153], v[48:49]
	v_pk_add_f32 v[50:51], v[66:67], v[50:51]
	v_pk_add_f32 v[60:61], v[150:151], v[60:61]
	v_pk_add_f32 v[52:53], v[68:69], v[52:53]
	v_pk_add_f32 v[48:49], v[50:51], v[48:49]
	v_pk_add_f32 v[50:51], v[70:71], v[54:55]
	v_pk_add_f32 v[52:53], v[52:53], v[60:61]
	v_pk_add_f32 v[60:61], v[136:137], v[78:79]
	v_pk_add_f32 v[48:49], v[50:51], v[48:49]
	v_pk_add_f32 v[50:51], v[72:73], v[56:57]
	v_pk_add_f32 v[52:53], v[60:61], v[52:53]
	v_pk_add_f32 v[58:59], v[74:75], v[58:59]
	v_pk_add_f32 v[152:153], v[50:51], v[48:49]
	v_pk_add_f32 v[150:151], v[58:59], v[52:53]
	s_waitcnt lgkmcnt(0)
	s_barrier
	ds_read_b128 v[48:51], v169
	ds_read_b128 v[52:55], v169 offset:32
	ds_read_b128 v[116:119], v169 offset:6656
	ds_read_b128 v[120:123], v169 offset:6688
	s_add_i32 m0, s70, 13312
	s_nop 0
	global_load_lds_dwordx4 v241, s[98:99]
	s_add_i32 m0, s73, s74
	global_load_dwordx4 v[112:115], v158, s[100:101] offset:640
	global_load_lds_dwordx4 v242, s[98:99]
	s_add_u32 s98, s98, 0x18000
	s_addc_u32 s99, s99, 0
	s_waitcnt lgkmcnt(3)
	v_mfma_f32_32x32x16_bf16 v[64:79], v[48:51], v[100:103], v[32:47]
	ds_read_b128 v[124:127], v169 offset:64
	ds_read_b128 v[128:131], v169 offset:96
	ds_read_b128 v[132:135], v169 offset:6720
	ds_read_b128 v[136:139], v169 offset:6752
	s_waitcnt lgkmcnt(4)
	v_mfma_f32_32x32x16_bf16 v[64:79], v[52:55], v[96:99], v[64:79]
	v_mfma_f32_32x32x16_bf16 v[48:63], v[116:119], v[100:103], v[32:47]
	v_mfma_f32_32x32x16_bf16 v[48:63], v[120:123], v[96:99], v[48:63]
	s_waitcnt lgkmcnt(1)
	v_mfma_f32_32x32x16_bf16 v[64:79], v[124:127], v[92:95], v[64:79]
	v_mfma_f32_32x32x16_bf16 v[48:63], v[132:135], v[92:95], v[48:63]
	v_mfma_f32_32x32x16_bf16 v[64:79], v[128:131], v[88:91], v[64:79]
	ds_read_b128 v[116:119], v169 offset:128
	ds_read_b128 v[120:123], v169 offset:160
	ds_read_b128 v[128:131], v169 offset:6784
	ds_read_b128 v[176:179], v169 offset:6816
	s_waitcnt lgkmcnt(3)
	v_mfma_f32_32x32x16_bf16 v[48:63], v[136:139], v[88:91], v[48:63]
	v_mfma_f32_32x32x16_bf16 v[64:79], v[116:119], v[84:87], v[64:79]
	ds_read_b128 v[136:139], v170 offset:26624
	ds_read_b128 v[124:127], v170 offset:26656
	s_waitcnt lgkmcnt(3)
	v_mfma_f32_32x32x16_bf16 v[48:63], v[128:131], v[84:87], v[48:63]
	v_mfma_f32_32x32x16_bf16 v[64:79], v[120:123], v[80:83], v[64:79]
	ds_read_b128 v[132:135], v170 offset:26688
	ds_read_b128 v[120:123], v170 offset:26720
	ds_read_b128 v[144:147], v170 offset:31232
	ds_read_b128 v[140:143], v170 offset:31264
	ds_read_b128 v[128:131], v170 offset:31296
	ds_read_b128 v[116:119], v170 offset:31328
	s_waitcnt lgkmcnt(8)
	v_mfma_f32_32x32x16_bf16 v[48:63], v[176:179], v[80:83], v[48:63]
	s_add_i32 s43, s43, 1
	s_nop 3
	v_exp_f32_e32 v160, v64
	v_exp_f32_e32 v161, v65
	v_exp_f32_e32 v64, v66
	v_exp_f32_e32 v65, v67
	v_exp_f32_e32 v68, v68
	v_exp_f32_e32 v69, v69
	v_exp_f32_e32 v66, v70
	v_exp_f32_e32 v67, v71
	v_cvt_pk_bf16_f32 v176, v160, v161
	v_cvt_pk_bf16_f32 v177, v64, v65
	v_cvt_pk_bf16_f32 v178, v68, v69
	v_cvt_pk_bf16_f32 v179, v66, v67
	v_exp_f32_e32 v70, v74
	v_exp_f32_e32 v71, v75
	s_waitcnt lgkmcnt(0)
	v_mfma_f32_32x32x16_bf16 v[16:31], v[136:139], v[176:179], v[16:31]
	v_exp_f32_e32 v136, v72
	v_exp_f32_e32 v137, v73
	v_exp_f32_e32 v74, v76
	v_exp_f32_e32 v75, v77
	v_exp_f32_e32 v72, v78
	v_exp_f32_e32 v73, v79
	v_exp_f32_e32 v76, v48
	v_mfma_f32_32x32x16_bf16 v[0:15], v[144:147], v[176:179], v[0:15]
	v_cvt_pk_bf16_f32 v144, v136, v137
	v_cvt_pk_bf16_f32 v145, v70, v71
	v_cvt_pk_bf16_f32 v146, v74, v75
	v_cvt_pk_bf16_f32 v147, v72, v73
	v_exp_f32_e32 v77, v49
	v_exp_f32_e32 v48, v50
	v_exp_f32_e32 v49, v51
	v_mfma_f32_32x32x16_bf16 v[16:31], v[124:127], v[144:147], v[16:31]
	v_exp_f32_e32 v52, v52
	v_exp_f32_e32 v53, v53
	v_exp_f32_e32 v50, v54
	v_exp_f32_e32 v51, v55
	v_cvt_pk_bf16_f32 v124, v76, v77
	v_cvt_pk_bf16_f32 v125, v48, v49
	v_cvt_pk_bf16_f32 v126, v52, v53
	v_mfma_f32_32x32x16_bf16 v[0:15], v[140:143], v[144:147], v[0:15]
	v_cvt_pk_bf16_f32 v127, v50, v51
	v_exp_f32_e32 v78, v56
	v_exp_f32_e32 v79, v57
	v_exp_f32_e32 v54, v58
	v_exp_f32_e32 v55, v59
	v_exp_f32_e32 v58, v60
	v_exp_f32_e32 v59, v61
	v_mfma_f32_32x32x16_bf16 v[16:31], v[132:135], v[124:127], v[16:31]
	v_exp_f32_e32 v56, v62
	v_exp_f32_e32 v57, v63
	v_cvt_pk_bf16_f32 v60, v78, v79
	v_cvt_pk_bf16_f32 v61, v54, v55
	v_cvt_pk_bf16_f32 v62, v58, v59
	v_cvt_pk_bf16_f32 v63, v56, v57
	v_mfma_f32_32x32x16_bf16 v[0:15], v[128:131], v[124:127], v[0:15]
	v_mfma_f32_32x32x16_bf16 v[16:31], v[120:123], v[60:63], v[16:31]
	v_mfma_f32_32x32x16_bf16 v[0:15], v[116:119], v[60:63], v[0:15]
	s_waitcnt vmcnt(0)
	ds_write2_b64 v246, v[112:113], v[114:115] offset1:2
	v_pk_add_f32 v[48:49], v[64:65], v[48:49]
	v_pk_add_f32 v[60:61], v[160:161], v[76:77]
	v_pk_add_f32 v[48:49], v[152:153], v[48:49]
	v_pk_add_f32 v[50:51], v[66:67], v[50:51]
	v_pk_add_f32 v[60:61], v[150:151], v[60:61]
	v_pk_add_f32 v[52:53], v[68:69], v[52:53]
	v_pk_add_f32 v[48:49], v[50:51], v[48:49]
	v_pk_add_f32 v[50:51], v[70:71], v[54:55]
	v_pk_add_f32 v[52:53], v[52:53], v[60:61]
	v_pk_add_f32 v[60:61], v[136:137], v[78:79]
	v_pk_add_f32 v[48:49], v[50:51], v[48:49]
	v_pk_add_f32 v[50:51], v[72:73], v[56:57]
	v_pk_add_f32 v[52:53], v[60:61], v[52:53]
	v_pk_add_f32 v[58:59], v[74:75], v[58:59]
	v_pk_add_f32 v[152:153], v[50:51], v[48:49]
	v_pk_add_f32 v[150:151], v[58:59], v[52:53]
	s_waitcnt lgkmcnt(0)
	s_barrier
	s_add_u32 s100, s100, 0x300
	s_addc_u32 s101, s101, 0
	s_branch .Lmla_loop
